# E17b: norm1+norm2 row loops: w/sc/sh loads issued up-front before next-row prefetch, counted waits
# baseline (speedup 1.0000x reference)
; __device__ __forceinline__ int tid_() { int t = threadIdx.x; asm volatile("" : "+v"(t)); return t; }
; __device__ __forceinline__ void norm_phase(float* __restrict__ X, bf16_t* __restrict__ H, const float* __restrict__ nw, const float* __restrict__ modL, const float* __restrict__ modC, int sh_off, int sc_off, ...
;   const int tid = tid_(); const int wid = tid >> 6, lane = tid & 63;
;   const int stride = gridDim.x * 8;
;   int r = blockIdx.x * 8 + wid;
;   f32x4 nx[4];
;     ...
;   if (r < T_TOK) { const float* sp = NSRC(r);
; #pragma unroll
;     for (int i = 0; i < 4; ++i) nx[i] = *(const f32x4*)(sp + i * 256 + lane * 4);
;   }
;     ...
; #pragma unroll
;     for (int i = 0; i < 4; ++i) ss += v[i][0] * v[i][0] + v[i][1] * v[i][1] + v[i][2] * v[i][2] + v[i][3] * v[i][3];
;     ss = wave_sum(ss); const float rstd = rsqrtf(ss * (1.f / DM) + EPSN);
.LBB0_534:
	s_or_b64 exec, exec, s[24:25]
	v_readlane_b32 s28, v255, 28
	v_readlane_b32 s29, v255, 29
	v_lshlrev_b32_e32 v2, 2, v4
	s_mov_b32 s29, s35
	v_and_b32_e32 v36, 0xfc, v2
	s_lshl_b64 s[24:25], s[28:29], 12
	v_lshlrev_b32_e32 v6, 2, v36
	v_mov_b32_e32 v7, v144
	s_waitcnt lgkmcnt(0)
	s_add_u32 s24, s22, s24
	v_lshl_add_u64 v[0:1], v[0:1], 0, v[6:7]
	s_addc_u32 s25, s23, s25
	global_load_dwordx4 v[28:31], v[0:1], off
	global_load_dwordx4 v[24:27], v[0:1], off offset:1024
	global_load_dwordx4 v[20:23], v[0:1], off offset:2048
	global_load_dwordx4 v[32:35], v[0:1], off offset:3072
	s_nop 0
	global_load_dwordx4 v[0:3], v6, s[24:25]
	s_mul_i32 s23, s28, 0x6000
	s_mul_hi_u32 s22, s28, 0x6000
	s_mov_b32 s36, s28
	s_add_u32 s20, s20, s23
	v_writelane_b32 v255, s36, 28
	s_addc_u32 s21, s21, s22
	v_lshl_add_u64 v[38:39], s[24:25], 0, v[6:7]
	v_writelane_b32 v255, s37, 29
	s_add_u32 s36, s20, 0x9b90000
	s_addc_u32 s37, s21, 0
	v_readlane_b32 s20, v255, 30
	v_readlane_b32 s21, v255, 31
	s_lshl_b64 s[20:21], s[20:21], 2
	s_add_u32 s18, s18, s20
	s_addc_u32 s19, s19, s21
	s_add_u32 s38, s18, 0x9b96000
	s_addc_u32 s39, s19, 0
	v_and_b32_e32 v7, 63, v4
	v_lshlrev_b64 v[12:13], 11, v[56:57]
	s_cmp_lg_u64 s[14:15], 0
	v_lshl_or_b32 v12, v7, 3, v12
	s_cselect_b64 s[20:21], -1, 0
	s_cmp_lg_u64 s[10:11], 0
	v_or_b32_e32 v6, 0x100, v36
	v_or_b32_e32 v8, 0x200, v36
	v_or_b32_e32 v10, 0x300, v36
	v_lshlrev_b64 v[4:5], 12, v[56:57]
	v_lshl_add_u64 v[12:13], s[6:7], 0, v[12:13]
	s_mov_b64 s[6:7], 0x4100000
	s_mov_b64 s[18:19], 0
	s_cselect_b64 s[22:23], -1, 0
	v_lshlrev_b32_e32 v40, 4, v7
	v_mov_b32_e32 v41, v144
	v_lshl_add_u64 v[42:43], s[26:27], 0, v[4:5]
	v_lshl_add_u64 v[44:45], v[12:13], 0, s[6:7]
	v_lshl_add_u64 v[46:47], s[8:9], 0, v[4:5]
	v_lshlrev_b32_e32 v48, 2, v6
	v_lshlrev_b32_e32 v50, 2, v8
	v_lshlrev_b32_e32 v52, 2, v10
	s_waitcnt vmcnt(1)
	s_branch .LBB0_536
.LBB0_535:
	s_or_b64 exec, exec, s[26:27]
	v_mul_f32_e32 v37, v29, v29
	v_mul_f32_e32 v49, v25, v25
	v_mul_f32_e32 v51, v21, v21
	v_fmac_f32_e32 v37, v28, v28
	v_fmac_f32_e32 v49, v24, v24
	v_mul_f32_e32 v53, v33, v33
	v_fmac_f32_e32 v51, v20, v20
	v_fmac_f32_e32 v37, v30, v30
	v_fmac_f32_e32 v49, v26, v26
	v_fmac_f32_e32 v53, v32, v32
	v_fmac_f32_e32 v51, v22, v22
	v_fmac_f32_e32 v37, v31, v31
	v_fmac_f32_e32 v49, v27, v27
	v_fmac_f32_e32 v53, v34, v34
	v_fmac_f32_e32 v51, v23, v23
	v_add_f32_e32 v37, v37, v49
	v_fmac_f32_e32 v53, v35, v35
	v_add_f32_e32 v37, v51, v37
	v_add_f32_e32 v37, v53, v37
	v_readlane_b32 s6, v255, 9
	v_readlane_b32 s7, v255, 10
	v_add_f32_dpp v37, v37, v37 quad_perm:[1,0,3,2] row_mask:0xf bank_mask:0xf bound_ctrl:1
	v_lshl_add_u64 v[42:43], v[42:43], 0, s[68:69]
	v_lshl_add_u64 v[46:47], v[46:47], 0, s[68:69]
	v_add_f32_dpp v37, v37, v37 quad_perm:[2,3,0,1] row_mask:0xf bank_mask:0xf bound_ctrl:1
	s_nop 1
	v_add_f32_dpp v37, v37, v37 row_ror:4 row_mask:0xf bank_mask:0xf bound_ctrl:1
	s_nop 1
	v_add_f32_dpp v37, v37, v37 row_ror:8 row_mask:0xf bank_mask:0xf bound_ctrl:1
	v_mov_b32_e32 v49, v37
	s_nop 1
	v_permlane16_swap_b32_e32 v37, v49
	v_add_f32_e32 v37, v37, v49
	v_mov_b32_e32 v49, v37
	s_nop 1
	v_permlane32_swap_b32_e32 v37, v49
	v_add_f32_e32 v37, v37, v49
	v_fmamk_f32 v37, v37, 0x3a800000, v186
	v_mul_f32_e32 v49, 0x4b800000, v37
	v_cmp_gt_f32_e32 vcc, s57, v37
	s_nop 1
	v_cndmask_b32_e32 v37, v37, v49, vcc
	v_rsq_f32_e32 v37, v37
	s_nop 0
	v_mul_f32_e32 v51, 0x45800000, v37
	v_cndmask_b32_e32 v37, v37, v51, vcc
	s_cmp_lg_u32 s32, 0
	s_cbranch_scc1 .Lnrm_pf_n1
	s_waitcnt vmcnt(0)
; __device__ __forceinline__ void store_bf16x4(bf16_t* p, f32x4 v) { u32x2 w; w.x = cvt_pk_bf16(v[0], v[1]); w.y = cvt_pk_bf16(v[2], v[3]); *(u32x2*)p = w; }
; __device__ __forceinline__ void norm_phase(float* __restrict__ X, bf16_t* __restrict__ H, const float* __restrict__ nw, const float* __restrict__ modL, const float* __restrict__ modC, int sh_off, int sc_off, ...
;     ...
;     const int rn = r + stride;
;     if (rn < T_TOK) { const float* sp = NSRC(rn);
; #pragma unroll
;       for (int i = 0; i < 4; ++i) nx[i] = *(const f32x4*)(sp + i * 256 + lane * 4);
;     }
;     if (r < NCTX && nsl > 0) {
;       for (int sl = 0; sl < nsl; ++sl) { const float* pr = part + ((size_t)sl * NCTX + r) * DM;
; #pragma unroll
;         for (int i = 0; i < 4; ++i) v[i] += *(const f32x4*)(pr + i * 256 + lane * 4); }
; #pragma unroll
;       for (int i = 0; i < 4; ++i) *(f32x4*)(xr + i * 256 + lane * 4) = v[i];
;     }
; #pragma unroll
;     for (int i = 0; i < 4; ++i) ss += v[i][0] * v[i][0] + v[i][1] * v[i][1] + v[i][2] * v[i][2] + v[i][3] * v[i][3];
;     ss = wave_sum(ss); const float rstd = rsqrtf(ss * (1.f / DM) + EPSN);
;     const float* md = r < NCTX ? modC : modL;
; #pragma unroll
;     for (int i = 0; i < 4; ++i) { const int col = i * 256 + lane * 4; const f32x4 w = *(const f32x4*)(nw + col), sc = *(const f32x4*)(md + sc_off + col), sh = *(const f32x4*)(md + sh_off + col);
;       f32x4 h; for (int j = 0; j < 4; ++j) h[j] = (v[i][j] * rstd) * w[j] * (1.f + sc[j]) + sh[j];
;       store_bf16x4(H + (size_t)r * DM + col, h); }
.Lnrm_pf_n1:
	s_waitcnt vmcnt(4)
	v_mul_f32_e32 v28, v28, v37
	v_mul_f32_e32 v29, v29, v37
	v_mul_f32_e32 v30, v30, v37
	v_mul_f32_e32 v31, v31, v37
	v_mul_f32_e32 v28, v0, v28
	v_mul_f32_e32 v29, v1, v29
	v_mul_f32_e32 v30, v2, v30
	v_mul_f32_e32 v31, v3, v31
	v_add_f32_e32 v162, 1.0, v162
	v_add_f32_e32 v163, 1.0, v163
	v_add_f32_e32 v164, 1.0, v164
	v_add_f32_e32 v165, 1.0, v165
	v_fma_f32 v28, v162, v28, v178
	v_fma_f32 v29, v163, v29, v179
	v_fma_f32 v30, v164, v30, v180
	v_fma_f32 v31, v165, v31, v181
	v_cvt_pk_bf16_f32 v60, v28, v29
	v_cvt_pk_bf16_f32 v61, v30, v31
	global_store_dwordx2 v[44:45], v[60:61], off
	v_mul_f32_e32 v24, v24, v37
	v_mul_f32_e32 v25, v25, v37
	v_mul_f32_e32 v26, v26, v37
	v_mul_f32_e32 v27, v27, v37
	v_mul_f32_e32 v24, v150, v24
	v_mul_f32_e32 v25, v151, v25
	v_mul_f32_e32 v26, v152, v26
	v_mul_f32_e32 v27, v153, v27
	v_add_f32_e32 v166, 1.0, v166
	v_add_f32_e32 v167, 1.0, v167
	v_add_f32_e32 v168, 1.0, v168
	v_add_f32_e32 v169, 1.0, v169
	v_fma_f32 v24, v166, v24, v182
	v_fma_f32 v25, v167, v25, v183
	v_fma_f32 v26, v168, v26, v184
	v_fma_f32 v27, v169, v27, v185
	v_cvt_pk_bf16_f32 v62, v24, v25
	v_cvt_pk_bf16_f32 v63, v26, v27
	global_store_dwordx2 v[44:45], v[62:63], off offset:512
	v_mul_f32_e32 v20, v20, v37
	v_mul_f32_e32 v21, v21, v37
	v_mul_f32_e32 v22, v22, v37
	v_mul_f32_e32 v23, v23, v37
	v_mul_f32_e32 v20, v154, v20
	v_mul_f32_e32 v21, v155, v21
	v_mul_f32_e32 v22, v156, v22
	v_mul_f32_e32 v23, v157, v23
	v_add_f32_e32 v170, 1.0, v170
	v_add_f32_e32 v171, 1.0, v171
	v_add_f32_e32 v172, 1.0, v172
	v_add_f32_e32 v173, 1.0, v173
	v_fma_f32 v20, v170, v20, v214
	v_fma_f32 v21, v171, v21, v215
	v_fma_f32 v22, v172, v22, v216
	v_fma_f32 v23, v173, v23, v217
	v_cvt_pk_bf16_f32 v64, v20, v21
	v_cvt_pk_bf16_f32 v65, v22, v23
	global_store_dwordx2 v[44:45], v[64:65], off offset:1024
	v_mul_f32_e32 v32, v32, v37
	v_mul_f32_e32 v33, v33, v37
	v_mul_f32_e32 v34, v34, v37
	v_mul_f32_e32 v35, v35, v37
	v_mul_f32_e32 v32, v158, v32
	v_mul_f32_e32 v33, v159, v33
	v_mul_f32_e32 v34, v160, v34
	v_mul_f32_e32 v35, v161, v35
	v_add_f32_e32 v174, 1.0, v174
	v_add_f32_e32 v175, 1.0, v175
	v_add_f32_e32 v176, 1.0, v176
	v_add_f32_e32 v177, 1.0, v177
	v_fma_f32 v32, v174, v32, v218
	v_fma_f32 v33, v175, v33, v219
	v_fma_f32 v34, v176, v34, v220
	v_fma_f32 v35, v177, v35, v221
	v_cvt_pk_bf16_f32 v66, v32, v33
	v_cvt_pk_bf16_f32 v67, v34, v35
	global_store_dwordx2 v[44:45], v[66:67], off offset:1536
	s_waitcnt vmcnt(4)
	v_mov_b32_e32 v28, v16
	v_mov_b32_e32 v29, v17
	v_mov_b32_e32 v30, v18
	v_mov_b32_e32 v31, v19
	v_mov_b32_e32 v24, v12
	v_mov_b32_e32 v25, v13
	v_mov_b32_e32 v26, v14
	v_mov_b32_e32 v27, v15
	v_mov_b32_e32 v20, v8
	v_mov_b32_e32 v21, v9
	v_mov_b32_e32 v22, v10
	v_mov_b32_e32 v23, v11
	v_mov_b32_e32 v32, v4
	v_mov_b32_e32 v33, v5
	v_mov_b32_e32 v34, v6
	v_mov_b32_e32 v35, v7
	v_mov_b32_e32 v56, v54
	v_lshl_add_u64 v[44:45], v[44:45], 0, s[6:7]
	s_andn2_b64 exec, exec, s[18:19]
	s_cbranch_execz .LBB0_550
.LBB0_536:
	v_add_u32_e32 v54, s50, v56
	v_cmp_gt_i32_e32 vcc, s86, v54
	v_cmp_lt_i32_e64 s[6:7], s79, v54
	v_cmp_gt_i32_e64 s[24:25], s73, v56
	v_mov_b32_e32 v222, s37
	v_mov_b32_e32 v223, s39
	v_cndmask_b32_e64 v225, v222, v223, s[24:25]
	v_mov_b32_e32 v222, s36
	v_mov_b32_e32 v223, s38
	v_cndmask_b32_e64 v224, v222, v223, s[24:25]
	v_lshlrev_b32_e32 v226, 2, v36
	v_mov_b32_e32 v227, v144
	v_lshl_add_u64 v[224:225], v[224:225], 0, v[226:227]
	s_mov_b64 s[24:25], 0x1000
	v_lshl_add_u64 v[228:229], v[224:225], 0, s[24:25]
	v_lshl_add_u64 v[230:231], v[224:225], 0, 0
	global_load_dwordx4 v[162:165], v[228:229], off
	global_load_dwordx4 v[178:181], v[230:231], off
	global_load_dwordx4 v[150:153], v[38:39], off offset:1024
	global_load_dwordx4 v[166:169], v[228:229], off offset:1024
	global_load_dwordx4 v[182:185], v[230:231], off offset:1024
	global_load_dwordx4 v[154:157], v[38:39], off offset:2048
	global_load_dwordx4 v[170:173], v[228:229], off offset:2048
	global_load_dwordx4 v[214:217], v[230:231], off offset:2048
	global_load_dwordx4 v[158:161], v[38:39], off offset:3072
	global_load_dwordx4 v[174:177], v[228:229], off offset:3072
	global_load_dwordx4 v[218:221], v[230:231], off offset:3072
	s_or_b32 s32, vcc_lo, vcc_hi
	s_and_saveexec_b64 s[26:27], vcc
	s_cbranch_execz .LBB0_546
	v_cmp_lt_i32_e32 vcc, s81, v54
	s_and_saveexec_b64 s[24:25], vcc
	s_xor_b64 s[24:25], exec, s[24:25]
	s_cbranch_execz .LBB0_541
	s_andn2_b64 vcc, exec, s[20:21]
	s_cbranch_vccnz .LBB0_548
	v_add_u32_e32 v4, 0xffffff00, v54
	v_mov_b32_e32 v5, v144
	v_lshlrev_b64 v[4:5], 12, v[4:5]
	v_lshl_add_u64 v[4:5], s[14:15], 0, v[4:5]
	s_cbranch_execnz .LBB0_541
